# v9 + out_proj epilogue residual x loads use cache policy sc1 nt instead of nt
# baseline (speedup 1.0000x reference)
;     __device__ __forceinline__ void operator()(f32x4 (&acc)[2][2][4][2], const Unit& u, int wr, int wc, int fr, int fq) const {
; #pragma unroll
;         for (int ai = 0; ai < 2; ++ai) {
;             f32x4 xv[4][2][2];
; #pragma unroll
;             for (int m = 0; m < 4; ++m) {
;                 const int row = 256 * u.pm + 128 * ai + 64 * wr + 16 * m + fr;
; #pragma unroll
;                 for (int bj = 0; bj < 2; ++bj)
; #pragma unroll
;                     for (int n = 0; n < 2; ++n) xv[m][bj][n] = __builtin_nontemporal_load((const f32x4*)(x + (size_t)row * 1024 + 256 * u.pn + 64 * wc + 32 * bj + 8 * fq + 4 * n));
;             }
; #pragma unroll
;             for (int m = 0; m < 4; ++m) {
;                 const int row = 256 * u.pm + 128 * ai + 64 * wr + 16 * m + fr;
;                 float ss = 0.f;
; #pragma unroll
;                 for (int bj = 0; bj < 2; ++bj)
; #pragma unroll
;                     for (int n = 0; n < 2; ++n) {
;                         const f32x4 v = acc[ai][bj][m][n] + xv[m][bj][n];
;                         acc[ai][bj][m][n] = v;
;                         ss += (v[0] * v[0] + v[1] * v[1]) + (v[2] * v[2] + v[3] * v[3]);
;                     }
;                 ss += __shfl_xor(ss, 16); ss += __shfl_xor(ss, 32);
;                 if (fq == 0) SSQ[row * 16 + 4 * u.pn + wc] = ss;
.LBB0_491:
	v_lshl_add_u32 v184, s8, 8, v186
	s_lshl_b32 s34, s10, 8
	s_ashr_i32 s35, s34, 31
	v_ashrrev_i32_e32 v185, 31, v184
	v_lshl_add_u64 v[182:183], s[34:35], 2, v[176:177]
	v_lshlrev_b64 v[128:129], 12, v[184:185]
	v_lshl_add_u64 v[128:129], v[182:183], 0, v[128:129]
	global_load_dwordx4 v[206:209], v[128:129], off sc1 nt
	global_load_dwordx4 v[210:213], v[128:129], off offset:16 sc1 nt
	global_load_dwordx4 v[214:217], v[128:129], off offset:128 sc1 nt
	global_load_dwordx4 v[218:221], v[128:129], off offset:144 sc1 nt
	v_or_b32_e32 v128, 16, v184
	v_or_b32_e32 v130, 32, v184
	v_or_b32_e32 v132, 48, v184
	v_ashrrev_i32_e32 v129, 31, v128
	v_ashrrev_i32_e32 v131, 31, v130
	v_ashrrev_i32_e32 v133, 31, v132
	v_lshlrev_b64 v[128:129], 12, v[128:129]
	v_lshlrev_b64 v[130:131], 12, v[130:131]
	v_lshlrev_b64 v[132:133], 12, v[132:133]
	v_lshl_add_u64 v[128:129], v[182:183], 0, v[128:129]
	v_lshl_add_u64 v[130:131], v[182:183], 0, v[130:131]
	v_lshl_add_u64 v[132:133], v[182:183], 0, v[132:133]
	global_load_dwordx4 v[168:171], v[128:129], off offset:16 sc1 nt
	global_load_dwordx4 v[172:175], v[128:129], off sc1 nt
	global_load_dwordx4 v[160:163], v[128:129], off offset:144 sc1 nt
	global_load_dwordx4 v[164:167], v[128:129], off offset:128 sc1 nt
	global_load_dwordx4 v[152:155], v[130:131], off offset:16 sc1 nt
	global_load_dwordx4 v[156:159], v[130:131], off sc1 nt
	global_load_dwordx4 v[144:147], v[130:131], off offset:144 sc1 nt
	global_load_dwordx4 v[148:151], v[130:131], off offset:128 sc1 nt
	global_load_dwordx4 v[136:139], v[132:133], off offset:16 sc1 nt
	global_load_dwordx4 v[140:143], v[132:133], off sc1 nt
	s_nop 0
	global_load_dwordx4 v[128:131], v[132:133], off offset:144 sc1 nt
	s_nop 0
	global_load_dwordx4 v[132:135], v[132:133], off offset:128 sc1 nt
	v_add_u32_e32 v240, 0x80, v184
	v_ashrrev_i32_e32 v241, 31, v240
	v_lshlrev_b64 v[240:241], 12, v[240:241]
	v_lshl_add_u64 v[240:241], v[182:183], 0, v[240:241]
	global_load_dwordx4 v[224:227], v[240:241], off sc1 nt
	global_load_dwordx4 v[228:231], v[240:241], off offset:16 sc1 nt
	global_load_dwordx4 v[232:235], v[240:241], off offset:128 sc1 nt
	global_load_dwordx4 v[236:239], v[240:241], off offset:144 sc1 nt
	v_xor_b32_e32 v185, 16, v192
	v_cmp_lt_i32_e32 vcc, v185, v202
	s_waitcnt vmcnt(4)
	v_pk_add_f32 v[126:127], v[126:127], v[208:209]
	v_pk_add_f32 v[124:125], v[124:125], v[206:207]
	v_pk_add_f32 v[122:123], v[122:123], v[212:213]
	v_pk_add_f32 v[120:121], v[120:121], v[210:211]
	v_pk_add_f32 v[118:119], v[118:119], v[216:217]
	v_pk_add_f32 v[116:117], v[116:117], v[214:215]
	v_mul_f32_e32 v206, v125, v125
	v_mul_f32_e32 v207, v127, v127
	v_mul_f32_e32 v208, v121, v121
	v_mul_f32_e32 v209, v123, v123
	v_pk_add_f32 v[114:115], v[114:115], v[220:221]
	v_pk_add_f32 v[112:113], v[112:113], v[218:219]
	v_mul_f32_e32 v210, v117, v117
	v_mul_f32_e32 v211, v119, v119
	v_fmac_f32_e32 v206, v124, v124
	v_fmac_f32_e32 v207, v126, v126
	v_fmac_f32_e32 v208, v120, v120
	v_fmac_f32_e32 v209, v122, v122
	v_mul_f32_e32 v212, v113, v113
	v_mul_f32_e32 v213, v115, v115
	v_fmac_f32_e32 v210, v116, v116
	v_fmac_f32_e32 v211, v118, v118
	v_add_f32_e32 v206, v206, v207
	v_add_f32_e32 v207, v208, v209
	v_fmac_f32_e32 v212, v112, v112
	v_fmac_f32_e32 v213, v114, v114
	v_add_f32_e32 v208, v210, v211
	v_add_f32_e32 v206, v206, v207
	v_cndmask_b32_e32 v185, v192, v185, vcc
	v_add_f32_e32 v206, v206, v208
	v_add_f32_e32 v207, v212, v213
	v_lshlrev_b32_e32 v185, 2, v185
	v_add_f32_e32 v207, v206, v207
	ds_bpermute_b32 v208, v185, v207
	v_cmp_lt_i32_e32 vcc, v193, v202
	s_waitcnt lgkmcnt(0)
	v_add_f32_e32 v207, v207, v208
	v_cndmask_b32_e32 v206, v192, v193, vcc
	v_lshlrev_b32_e32 v206, 2, v206
	ds_bpermute_b32 v208, v206, v207
	s_and_saveexec_b64 s[34:35], s[4:5]
	s_cbranch_execz .LBB0_493
	s_lshl_b32 s19, s8, 12
	s_lshl_b32 s21, s10, 2
	s_add_i32 s19, s19, s21
	s_waitcnt lgkmcnt(0)
	v_add_f32_e32 v207, v207, v208
	v_add_u32_e32 v208, s19, v188
	v_ashrrev_i32_e32 v209, 31, v208
	v_lshl_add_u64 v[208:209], v[208:209], 2, s[6:7]
	global_store_dword v[208:209], v207, off

;     __device__ __forceinline__ void operator()(f32x4 (&acc)[2][2][4][2], const Unit& u, int wr, int wc, int fr, int fq) const {
; #pragma unroll
;         for (int ai = 0; ai < 2; ++ai) {
;             f32x4 xv[4][2][2];
; #pragma unroll
;             for (int m = 0; m < 4; ++m) {
;                 const int row = 256 * u.pm + 128 * ai + 64 * wr + 16 * m + fr;
; #pragma unroll
;                 for (int bj = 0; bj < 2; ++bj)
; #pragma unroll
;                     for (int n = 0; n < 2; ++n) xv[m][bj][n] = __builtin_nontemporal_load((const f32x4*)(x + (size_t)row * 1024 + 256 * u.pn + 64 * wc + 32 * bj + 8 * fq + 4 * n));
;             }
; #pragma unroll
;             for (int m = 0; m < 4; ++m) {
;                 const int row = 256 * u.pm + 128 * ai + 64 * wr + 16 * m + fr;
;                 float ss = 0.f;
; #pragma unroll
;                 for (int bj = 0; bj < 2; ++bj)
; #pragma unroll
;                     for (int n = 0; n < 2; ++n) {
;                         const f32x4 v = acc[ai][bj][m][n] + xv[m][bj][n];
;                         acc[ai][bj][m][n] = v;
;                         ss += (v[0] * v[0] + v[1] * v[1]) + (v[2] * v[2] + v[3] * v[3]);
;                     }
;                 ss += __shfl_xor(ss, 16); ss += __shfl_xor(ss, 32);
;                 if (fq == 0) SSQ[row * 16 + 4 * u.pn + wc] = ss;
.LBB0_495:
	s_or_b64 exec, exec, s[34:35]
	v_add_u32_e32 v242, 0x90, v184
	v_ashrrev_i32_e32 v243, 31, v242
	v_lshlrev_b64 v[242:243], 12, v[242:243]
	v_lshl_add_u64 v[242:243], v[182:183], 0, v[242:243]
	global_load_dwordx4 v[168:171], v[242:243], off offset:16 sc1 nt
	global_load_dwordx4 v[172:175], v[242:243], off sc1 nt
	global_load_dwordx4 v[160:163], v[242:243], off offset:144 sc1 nt
	global_load_dwordx4 v[164:167], v[242:243], off offset:128 sc1 nt
	v_pk_add_f32 v[94:95], v[94:95], v[158:159]
	v_pk_add_f32 v[92:93], v[92:93], v[156:157]
	v_pk_add_f32 v[90:91], v[90:91], v[154:155]
	v_pk_add_f32 v[88:89], v[88:89], v[152:153]
	v_mul_f32_e32 v156, v93, v93
	v_mul_f32_e32 v157, v95, v95
	v_mul_f32_e32 v152, v89, v89
	v_mul_f32_e32 v153, v91, v91
	v_pk_add_f32 v[86:87], v[86:87], v[150:151]
	v_pk_add_f32 v[84:85], v[84:85], v[148:149]
	v_fmac_f32_e32 v156, v92, v92
	v_fmac_f32_e32 v157, v94, v94
	v_fmac_f32_e32 v152, v88, v88
	v_fmac_f32_e32 v153, v90, v90
	v_mul_f32_e32 v148, v85, v85
	v_mul_f32_e32 v149, v87, v87
	v_pk_add_f32 v[82:83], v[82:83], v[146:147]
	v_pk_add_f32 v[80:81], v[80:81], v[144:145]
	v_add_f32_e32 v156, v156, v157
	v_add_f32_e32 v152, v152, v153
	v_fmac_f32_e32 v148, v84, v84
	v_fmac_f32_e32 v149, v86, v86
	v_mul_f32_e32 v144, v81, v81
	v_mul_f32_e32 v145, v83, v83
	v_add_f32_e32 v152, v156, v152
	v_add_f32_e32 v148, v148, v149
	v_fmac_f32_e32 v144, v80, v80
	v_fmac_f32_e32 v145, v82, v82
	v_add_f32_e32 v148, v152, v148
	v_add_f32_e32 v144, v144, v145
	v_add_f32_e32 v144, v148, v144
	ds_bpermute_b32 v145, v185, v144
	s_waitcnt lgkmcnt(0)
	v_add_f32_e32 v144, v144, v145
	ds_bpermute_b32 v145, v206, v144
	s_and_saveexec_b64 s[34:35], s[4:5]
	s_cbranch_execz .LBB0_497
	s_lshl_b32 s19, s8, 12
	s_lshl_b32 s21, s10, 2
	s_add_i32 s19, s19, s21
	s_waitcnt lgkmcnt(0)
	v_add_f32_e32 v146, v144, v145
	v_add_u32_e32 v144, s19, v190
	v_ashrrev_i32_e32 v145, 31, v144
	v_lshl_add_u64 v[144:145], v[144:145], 2, s[6:7]
	global_store_dword v[144:145], v146, off
.LBB0_497:
	s_or_b64 exec, exec, s[34:35]
	v_add_u32_e32 v244, 0xa0, v184
	v_ashrrev_i32_e32 v245, 31, v244
	v_lshlrev_b64 v[244:245], 12, v[244:245]
	v_lshl_add_u64 v[244:245], v[182:183], 0, v[244:245]
	global_load_dwordx4 v[152:155], v[244:245], off offset:16 sc1 nt
	global_load_dwordx4 v[156:159], v[244:245], off sc1 nt
	global_load_dwordx4 v[144:147], v[244:245], off offset:144 sc1 nt
	global_load_dwordx4 v[148:151], v[244:245], off offset:128 sc1 nt
	v_pk_add_f32 v[78:79], v[78:79], v[142:143]
	v_pk_add_f32 v[76:77], v[76:77], v[140:141]
	v_pk_add_f32 v[74:75], v[74:75], v[138:139]
	v_pk_add_f32 v[72:73], v[72:73], v[136:137]
	v_mul_f32_e32 v140, v77, v77
	v_mul_f32_e32 v141, v79, v79
	v_mul_f32_e32 v136, v73, v73
	v_mul_f32_e32 v137, v75, v75
	v_pk_add_f32 v[70:71], v[70:71], v[134:135]
	v_pk_add_f32 v[68:69], v[68:69], v[132:133]
	v_fmac_f32_e32 v140, v76, v76
	v_fmac_f32_e32 v141, v78, v78
	v_fmac_f32_e32 v136, v72, v72
	v_fmac_f32_e32 v137, v74, v74
	v_mul_f32_e32 v132, v69, v69
	v_mul_f32_e32 v133, v71, v71
	v_pk_add_f32 v[66:67], v[66:67], v[130:131]
	v_pk_add_f32 v[64:65], v[64:65], v[128:129]
	v_add_f32_e32 v140, v140, v141
	v_add_f32_e32 v136, v136, v137
	v_fmac_f32_e32 v132, v68, v68
	v_fmac_f32_e32 v133, v70, v70
	v_mul_f32_e32 v128, v65, v65
	v_mul_f32_e32 v129, v67, v67
	v_add_f32_e32 v136, v140, v136
	v_add_f32_e32 v132, v132, v133
	v_fmac_f32_e32 v128, v64, v64
	v_fmac_f32_e32 v129, v66, v66
	v_add_f32_e32 v132, v136, v132
	v_add_f32_e32 v128, v128, v129
	v_add_f32_e32 v128, v132, v128
	ds_bpermute_b32 v129, v185, v128
	s_waitcnt lgkmcnt(0)
	v_add_f32_e32 v128, v128, v129
	ds_bpermute_b32 v129, v206, v128
	s_and_saveexec_b64 s[34:35], s[4:5]
	s_cbranch_execz .LBB0_499
	s_lshl_b32 s19, s8, 12
	s_lshl_b32 s21, s10, 2
	s_add_i32 s19, s19, s21
	s_waitcnt lgkmcnt(0)
	v_add_f32_e32 v130, v128, v129
	v_add_u32_e32 v128, s19, v191
	v_ashrrev_i32_e32 v129, 31, v128
	v_lshl_add_u64 v[128:129], v[128:129], 2, s[6:7]
	global_store_dword v[128:129], v130, off
.LBB0_499:
	s_or_b64 exec, exec, s[34:35]
	v_add_u32_e32 v128, 0x80, v184
	s_waitcnt lgkmcnt(0)
	v_ashrrev_i32_e32 v129, 31, v128
	v_lshlrev_b64 v[128:129], 12, v[128:129]
	v_lshl_add_u64 v[128:129], v[182:183], 0, v[128:129]
	v_add_u32_e32 v128, 0x90, v184
	v_add_u32_e32 v130, 0xa0, v184
	v_add_u32_e32 v132, 0xb0, v184
	v_ashrrev_i32_e32 v129, 31, v128
	v_ashrrev_i32_e32 v131, 31, v130
	v_ashrrev_i32_e32 v133, 31, v132
	v_lshlrev_b64 v[128:129], 12, v[128:129]
	v_lshlrev_b64 v[130:131], 12, v[130:131]
	v_lshlrev_b64 v[132:133], 12, v[132:133]
	v_lshl_add_u64 v[128:129], v[182:183], 0, v[128:129]
	v_lshl_add_u64 v[130:131], v[182:183], 0, v[130:131]
	v_lshl_add_u64 v[132:133], v[182:183], 0, v[132:133]
	global_load_dwordx4 v[136:139], v[132:133], off offset:16 sc1 nt
	global_load_dwordx4 v[140:143], v[132:133], off sc1 nt
	s_nop 0
	global_load_dwordx4 v[128:131], v[132:133], off offset:144 sc1 nt
	s_nop 0
	global_load_dwordx4 v[132:135], v[132:133], off offset:128 sc1 nt
	s_waitcnt vmcnt(15)
	v_pk_add_f32 v[62:63], v[62:63], v[226:227]
	v_pk_add_f32 v[60:61], v[60:61], v[224:225]
	s_waitcnt vmcnt(14)
	v_pk_add_f32 v[58:59], v[58:59], v[230:231]
	v_pk_add_f32 v[56:57], v[56:57], v[228:229]
	s_waitcnt vmcnt(13)
	v_pk_add_f32 v[54:55], v[54:55], v[234:235]
	v_pk_add_f32 v[52:53], v[52:53], v[232:233]
	v_mul_f32_e32 v182, v61, v61
	v_mul_f32_e32 v183, v63, v63
	v_mul_f32_e32 v184, v57, v57
	v_mul_f32_e32 v207, v59, v59
	s_waitcnt vmcnt(12)
	v_pk_add_f32 v[50:51], v[50:51], v[238:239]
	v_pk_add_f32 v[48:49], v[48:49], v[236:237]
	v_mul_f32_e32 v208, v53, v53
	v_mul_f32_e32 v209, v55, v55
	v_fmac_f32_e32 v182, v60, v60
	v_fmac_f32_e32 v183, v62, v62
	v_fmac_f32_e32 v184, v56, v56
	v_fmac_f32_e32 v207, v58, v58
	v_mul_f32_e32 v210, v49, v49
	v_mul_f32_e32 v211, v51, v51
	v_fmac_f32_e32 v208, v52, v52
	v_fmac_f32_e32 v209, v54, v54
	v_add_f32_e32 v182, v182, v183
	v_add_f32_e32 v183, v184, v207
	v_fmac_f32_e32 v210, v48, v48
	v_fmac_f32_e32 v211, v50, v50
	v_add_f32_e32 v184, v208, v209
	v_add_f32_e32 v182, v182, v183
	v_add_f32_e32 v182, v182, v184
	v_add_f32_e32 v183, v210, v211
	v_add_f32_e32 v182, v182, v183
	ds_bpermute_b32 v183, v185, v182
	s_waitcnt lgkmcnt(0)
	v_add_f32_e32 v182, v182, v183
	ds_bpermute_b32 v183, v206, v182
	s_and_saveexec_b64 s[34:35], s[4:5]
	s_cbranch_execz .LBB0_501
	s_lshl_b32 s19, s8, 12
	s_lshl_b32 s21, s10, 2
	s_add_i32 s19, s19, s21
	s_waitcnt lgkmcnt(0)
	v_add_f32_e32 v184, v182, v183
	v_add_u32_e32 v182, s19, v200
	v_ashrrev_i32_e32 v183, 31, v182
	v_lshl_add_u64 v[182:183], v[182:183], 2, s[6:7]
	global_store_dword v[182:183], v184, off
